# v40 + gate/up K loop: all 16 LDS-DMA loads per iteration in SGPR-base (saddr) form, 16 64-bit VALU address adds per iteration removed (phase-4 bases re-derived with SALU)
# baseline (speedup 1.0000x reference)
.LBB0_145:
	s_ashr_i32 s17, s16, 31
	s_lshl_b64 s[18:19], s[16:17], 19
	s_add_u32 s18, s36, s18
	s_addc_u32 s19, s37, s19
	s_and_b64 s[20:21], s[2:3], exec
	s_cselect_b32 s17, s19, s25
	s_cselect_b32 s50, s18, s24
	s_ashr_i32 s15, s14, 31
	s_lshl_b64 s[20:21], s[14:15], 19
	s_add_u32 s20, s34, s20
	s_addc_u32 s21, s35, s21
	s_and_b64 s[28:29], s[2:3], exec
	s_cselect_b32 s15, s21, s27
	s_cselect_b32 s51, s20, s26
	s_add_u32 s24, s24, 0x40080
	s_addc_u32 s25, s25, 0
	s_add_u32 s52, s26, 0x100
	s_addc_u32 s53, s27, 0
	s_mov_b32 s54, -2
	s_add_u32 s26, s24, 0xfffc0080
	s_addc_u32 s27, s25, -1
	s_add_i32 s55, 0, 0x10000
	s_cmp_eq_u32 s54, 12
	s_cselect_b32 s29, s17, s27
	s_cselect_b32 s28, s50, s26
	v_add_u32_e32 v140, s55, v143
	s_cselect_b32 s27, s15, s53
	s_cselect_b32 s26, s51, s52
	s_add_i32 s60, 0, 0x14000
	ds_read_b128 v[150:153], v140
	ds_read_b128 v[154:157], v140 offset:1024
	ds_read_b128 v[158:161], v140 offset:2048
	ds_read_b128 v[162:165], v140 offset:3072
	v_add_u32_e32 v140, s60, v143
	ds_read_b128 v[166:169], v140
	ds_read_b128 v[170:173], v140 offset:1024
	ds_read_b128 v[174:177], v140 offset:2048
	ds_read_b128 v[178:181], v140 offset:3072
	s_add_i32 m0, s40, 0xc000
	ds_read_b128 v[182:185], v148
	ds_read_b128 v[186:189], v148 offset:1024
	ds_read_b128 v[190:193], v148 offset:2048
	ds_read_b128 v[202:205], v148 offset:3072
	ds_read_b128 v[206:209], v148 offset:4096
	ds_read_b128 v[210:213], v148 offset:5120
	ds_read_b128 v[214:217], v148 offset:6144
	ds_read_b128 v[218:221], v148 offset:7168
	global_load_lds_dwordx4 v136, s[24:25]
	s_add_i32 m0, s40, 0xe000
	s_nop 0
	global_load_lds_dwordx4 v138, s[24:25]
	s_waitcnt lgkmcnt(0)
	s_barrier
	s_setprio 1
	s_waitcnt lgkmcnt(0)
	v_mfma_f32_16x16x32_bf16 v[126:129], v[150:153], v[182:185], 0
	v_mfma_f32_16x16x32_bf16 v[118:121], v[158:161], v[182:185], 0
	v_mfma_f32_16x16x32_bf16 v[110:113], v[150:153], v[190:193], 0
	v_mfma_f32_16x16x32_bf16 v[102:105], v[158:161], v[190:193], 0
	v_mfma_f32_16x16x32_bf16 v[92:95], v[150:153], v[206:209], 0
	v_mfma_f32_16x16x32_bf16 v[84:87], v[158:161], v[206:209], 0
	v_mfma_f32_16x16x32_bf16 v[76:79], v[150:153], v[214:217], 0
	v_mfma_f32_16x16x32_bf16 v[68:71], v[158:161], v[214:217], 0
	v_mfma_f32_16x16x32_bf16 v[126:129], v[154:157], v[186:189], v[126:129]
	v_mfma_f32_16x16x32_bf16 v[118:121], v[162:165], v[186:189], v[118:121]
	v_mfma_f32_16x16x32_bf16 v[110:113], v[154:157], v[202:205], v[110:113]
	v_mfma_f32_16x16x32_bf16 v[102:105], v[162:165], v[202:205], v[102:105]
	v_mfma_f32_16x16x32_bf16 v[92:95], v[154:157], v[210:213], v[92:95]
	v_mfma_f32_16x16x32_bf16 v[84:87], v[162:165], v[210:213], v[84:87]
	v_mfma_f32_16x16x32_bf16 v[76:79], v[154:157], v[218:221], v[76:79]
	v_mfma_f32_16x16x32_bf16 v[68:71], v[162:165], v[218:221], v[68:71]
	s_setprio 0
	s_setprio 1
	v_mfma_f32_16x16x32_bf16 v[122:125], v[166:169], v[182:185], 0
	v_mfma_f32_16x16x32_bf16 v[114:117], v[174:177], v[182:185], 0
	v_mfma_f32_16x16x32_bf16 v[106:109], v[166:169], v[190:193], 0
	v_mfma_f32_16x16x32_bf16 v[98:101], v[174:177], v[190:193], 0
	v_mfma_f32_16x16x32_bf16 v[88:91], v[166:169], v[206:209], 0
	v_mfma_f32_16x16x32_bf16 v[80:83], v[174:177], v[206:209], 0
	v_mfma_f32_16x16x32_bf16 v[72:75], v[166:169], v[214:217], 0
	v_mfma_f32_16x16x32_bf16 v[64:67], v[174:177], v[214:217], 0
	v_mfma_f32_16x16x32_bf16 v[122:125], v[170:173], v[186:189], v[122:125]
	v_mfma_f32_16x16x32_bf16 v[114:117], v[178:181], v[186:189], v[114:117]
	v_mfma_f32_16x16x32_bf16 v[106:109], v[170:173], v[202:205], v[106:109]
	v_mfma_f32_16x16x32_bf16 v[98:101], v[178:181], v[202:205], v[98:101]
	v_mfma_f32_16x16x32_bf16 v[88:91], v[170:173], v[210:213], v[88:91]
	v_mfma_f32_16x16x32_bf16 v[80:83], v[178:181], v[210:213], v[80:83]
	v_mfma_f32_16x16x32_bf16 v[72:75], v[170:173], v[218:221], v[72:75]
	v_mfma_f32_16x16x32_bf16 v[64:67], v[178:181], v[218:221], v[64:67]
	s_setprio 0
	s_barrier
	s_add_i32 s55, s55, s39
	s_mov_b32 m0, s55
	ds_read_b128 v[182:185], v148 offset:16384
	ds_read_b128 v[186:189], v148 offset:17408
	ds_read_b128 v[190:193], v148 offset:18432
	ds_read_b128 v[202:205], v148 offset:19456
	ds_read_b128 v[206:209], v148 offset:20480
	ds_read_b128 v[210:213], v148 offset:21504
	ds_read_b128 v[214:217], v148 offset:22528
	ds_read_b128 v[218:221], v148 offset:23552
	global_load_lds_dwordx4 v96, s[26:27]
	s_add_i32 m0, s55, 0x2000
	s_add_u32 s56, s26, 0x40000
	s_addc_u32 s57, s27, 0
	s_add_i32 s55, s60, s39
	global_load_lds_dwordx4 v130, s[26:27]
	s_mov_b32 m0, s55
	s_nop 0
	global_load_lds_dwordx4 v96, s[56:57]
	s_add_i32 m0, s55, 0x2000
	s_nop 0
	global_load_lds_dwordx4 v130, s[56:57]
	s_mov_b32 m0, s40
	s_nop 0
	global_load_lds_dwordx4 v134, s[28:29]
	s_mov_b32 m0, s41
	s_nop 0
	global_load_lds_dwordx4 v132, s[28:29]
	s_waitcnt lgkmcnt(0)
	s_barrier
	s_setprio 1
	s_waitcnt lgkmcnt(0)
	v_mfma_f32_16x16x32_bf16 v[60:63], v[150:153], v[182:185], 0
	v_mfma_f32_16x16x32_bf16 v[52:55], v[158:161], v[182:185], 0
	v_mfma_f32_16x16x32_bf16 v[44:47], v[150:153], v[190:193], 0
	v_mfma_f32_16x16x32_bf16 v[36:39], v[158:161], v[190:193], 0
	v_mfma_f32_16x16x32_bf16 v[28:31], v[150:153], v[206:209], 0
	v_mfma_f32_16x16x32_bf16 v[20:23], v[158:161], v[206:209], 0
	v_mfma_f32_16x16x32_bf16 v[12:15], v[150:153], v[214:217], 0
	v_mfma_f32_16x16x32_bf16 v[4:7], v[158:161], v[214:217], 0
	v_mfma_f32_16x16x32_bf16 v[60:63], v[154:157], v[186:189], v[60:63]
	v_mfma_f32_16x16x32_bf16 v[52:55], v[162:165], v[186:189], v[52:55]
	v_mfma_f32_16x16x32_bf16 v[44:47], v[154:157], v[202:205], v[44:47]
	v_mfma_f32_16x16x32_bf16 v[36:39], v[162:165], v[202:205], v[36:39]
	v_mfma_f32_16x16x32_bf16 v[28:31], v[154:157], v[210:213], v[28:31]
	v_mfma_f32_16x16x32_bf16 v[20:23], v[162:165], v[210:213], v[20:23]
	v_mfma_f32_16x16x32_bf16 v[12:15], v[154:157], v[218:221], v[12:15]
	v_mfma_f32_16x16x32_bf16 v[4:7], v[162:165], v[218:221], v[4:7]
	s_setprio 0
	s_setprio 1
	v_mfma_f32_16x16x32_bf16 v[56:59], v[166:169], v[182:185], 0
	v_mfma_f32_16x16x32_bf16 v[48:51], v[174:177], v[182:185], 0
	v_mfma_f32_16x16x32_bf16 v[40:43], v[166:169], v[190:193], 0
	v_mfma_f32_16x16x32_bf16 v[32:35], v[174:177], v[190:193], 0
	v_mfma_f32_16x16x32_bf16 v[24:27], v[166:169], v[206:209], 0
	v_mfma_f32_16x16x32_bf16 v[16:19], v[174:177], v[206:209], 0
	v_mfma_f32_16x16x32_bf16 v[8:11], v[166:169], v[214:217], 0
	v_mfma_f32_16x16x32_bf16 v[0:3], v[174:177], v[214:217], 0
	v_mfma_f32_16x16x32_bf16 v[56:59], v[170:173], v[186:189], v[56:59]
	v_mfma_f32_16x16x32_bf16 v[48:51], v[178:181], v[186:189], v[48:51]
	v_mfma_f32_16x16x32_bf16 v[40:43], v[170:173], v[202:205], v[40:43]
	v_mfma_f32_16x16x32_bf16 v[32:35], v[178:181], v[202:205], v[32:35]
	v_mfma_f32_16x16x32_bf16 v[24:27], v[170:173], v[210:213], v[24:27]
	v_mfma_f32_16x16x32_bf16 v[16:19], v[178:181], v[210:213], v[16:19]
	v_mfma_f32_16x16x32_bf16 v[8:11], v[170:173], v[218:221], v[8:11]
	v_mfma_f32_16x16x32_bf16 v[0:3], v[178:181], v[218:221], v[0:3]
	s_setprio 0
	s_barrier
	s_add_i32 s55, 0, 0x18000
	v_add_u32_e32 v149, s55, v143
	s_add_i32 s56, 0, 0x1c000
	ds_read_b128 v[150:153], v149
	ds_read_b128 v[154:157], v149 offset:1024
	ds_read_b128 v[158:161], v149 offset:2048
	ds_read_b128 v[162:165], v149 offset:3072
	v_add_u32_e32 v149, s56, v143
	ds_read_b128 v[166:169], v149
	ds_read_b128 v[170:173], v149 offset:1024
	ds_read_b128 v[174:177], v149 offset:2048
	ds_read_b128 v[178:181], v149 offset:3072
	s_add_u32 s28, s28, 0x40000
	s_addc_u32 s29, s29, 0
	s_mov_b32 m0, s42
	ds_read_b128 v[182:185], v148 offset:32768
	ds_read_b128 v[186:189], v148 offset:33792
	ds_read_b128 v[190:193], v148 offset:34816
	ds_read_b128 v[202:205], v148 offset:35840
	ds_read_b128 v[206:209], v148 offset:36864
	ds_read_b128 v[210:213], v148 offset:37888
	ds_read_b128 v[214:217], v148 offset:38912
	ds_read_b128 v[218:221], v148 offset:39936
	global_load_lds_dwordx4 v134, s[28:29]
	s_mov_b32 m0, s43
	s_nop 0
	global_load_lds_dwordx4 v132, s[28:29]
	s_waitcnt vmcnt(8)
	s_waitcnt lgkmcnt(0)
	s_barrier
	s_setprio 1
	s_waitcnt lgkmcnt(0)
	v_mfma_f32_16x16x32_bf16 v[126:129], v[150:153], v[182:185], v[126:129]
	v_mfma_f32_16x16x32_bf16 v[118:121], v[158:161], v[182:185], v[118:121]
	v_mfma_f32_16x16x32_bf16 v[110:113], v[150:153], v[190:193], v[110:113]
	v_mfma_f32_16x16x32_bf16 v[102:105], v[158:161], v[190:193], v[102:105]
	v_mfma_f32_16x16x32_bf16 v[92:95], v[150:153], v[206:209], v[92:95]
	v_mfma_f32_16x16x32_bf16 v[84:87], v[158:161], v[206:209], v[84:87]
	v_mfma_f32_16x16x32_bf16 v[76:79], v[150:153], v[214:217], v[76:79]
	v_mfma_f32_16x16x32_bf16 v[68:71], v[158:161], v[214:217], v[68:71]
	v_mfma_f32_16x16x32_bf16 v[126:129], v[154:157], v[186:189], v[126:129]
	v_mfma_f32_16x16x32_bf16 v[118:121], v[162:165], v[186:189], v[118:121]
	v_mfma_f32_16x16x32_bf16 v[110:113], v[154:157], v[202:205], v[110:113]
	v_mfma_f32_16x16x32_bf16 v[102:105], v[162:165], v[202:205], v[102:105]
	v_mfma_f32_16x16x32_bf16 v[92:95], v[154:157], v[210:213], v[92:95]
	v_mfma_f32_16x16x32_bf16 v[84:87], v[162:165], v[210:213], v[84:87]
	v_mfma_f32_16x16x32_bf16 v[76:79], v[154:157], v[218:221], v[76:79]
	v_mfma_f32_16x16x32_bf16 v[68:71], v[162:165], v[218:221], v[68:71]
	s_setprio 0
	s_setprio 1
	v_mfma_f32_16x16x32_bf16 v[122:125], v[166:169], v[182:185], v[122:125]
	v_mfma_f32_16x16x32_bf16 v[114:117], v[174:177], v[182:185], v[114:117]
	v_mfma_f32_16x16x32_bf16 v[106:109], v[166:169], v[190:193], v[106:109]
	v_mfma_f32_16x16x32_bf16 v[98:101], v[174:177], v[190:193], v[98:101]
	v_mfma_f32_16x16x32_bf16 v[88:91], v[166:169], v[206:209], v[88:91]
	v_mfma_f32_16x16x32_bf16 v[80:83], v[174:177], v[206:209], v[80:83]
	v_mfma_f32_16x16x32_bf16 v[72:75], v[166:169], v[214:217], v[72:75]
	v_mfma_f32_16x16x32_bf16 v[64:67], v[174:177], v[214:217], v[64:67]
	v_mfma_f32_16x16x32_bf16 v[122:125], v[170:173], v[186:189], v[122:125]
	v_mfma_f32_16x16x32_bf16 v[114:117], v[178:181], v[186:189], v[114:117]
	v_mfma_f32_16x16x32_bf16 v[106:109], v[170:173], v[202:205], v[106:109]
	v_mfma_f32_16x16x32_bf16 v[98:101], v[178:181], v[202:205], v[98:101]
	v_mfma_f32_16x16x32_bf16 v[88:91], v[170:173], v[210:213], v[88:91]
	v_mfma_f32_16x16x32_bf16 v[80:83], v[178:181], v[210:213], v[80:83]
	v_mfma_f32_16x16x32_bf16 v[72:75], v[170:173], v[218:221], v[72:75]
	v_mfma_f32_16x16x32_bf16 v[64:67], v[178:181], v[218:221], v[64:67]
	s_setprio 0
	s_barrier
	s_add_u32 s98, s28, 0xfffc0080
	s_addc_u32 s99, s29, -1
	s_add_i32 s28, s55, s39
	s_add_u32 s26, s26, 0x80
	s_addc_u32 s27, s27, 0
	s_mov_b32 m0, s28
	ds_read_b128 v[182:185], v148 offset:49152
	ds_read_b128 v[186:189], v148 offset:50176
	ds_read_b128 v[190:193], v148 offset:51200
	ds_read_b128 v[202:205], v148 offset:52224
	ds_read_b128 v[206:209], v148 offset:53248
	ds_read_b128 v[210:213], v148 offset:54272
	ds_read_b128 v[214:217], v148 offset:55296
	ds_read_b128 v[218:221], v148 offset:56320
	global_load_lds_dwordx4 v96, s[26:27]
	s_add_i32 m0, s28, 0x2000
	s_add_i32 s28, s56, s39
	global_load_lds_dwordx4 v130, s[26:27]
	s_add_u32 s26, s26, 0x40000
	s_addc_u32 s27, s27, 0
	s_mov_b32 m0, s28
	s_nop 0
	global_load_lds_dwordx4 v96, s[26:27]
	s_add_i32 m0, s28, 0x2000
	s_nop 0
	global_load_lds_dwordx4 v130, s[26:27]
	s_mov_b32 m0, s44
	s_nop 0
	global_load_lds_dwordx4 v134, s[98:99]
	s_mov_b32 m0, s45
	s_nop 0
	global_load_lds_dwordx4 v132, s[98:99]
	s_waitcnt vmcnt(8)
	s_waitcnt lgkmcnt(0)
	s_barrier
	s_setprio 1
	s_waitcnt lgkmcnt(0)
	v_mfma_f32_16x16x32_bf16 v[60:63], v[150:153], v[182:185], v[60:63]
	v_mfma_f32_16x16x32_bf16 v[52:55], v[158:161], v[182:185], v[52:55]
	v_mfma_f32_16x16x32_bf16 v[44:47], v[150:153], v[190:193], v[44:47]
	v_mfma_f32_16x16x32_bf16 v[36:39], v[158:161], v[190:193], v[36:39]
	v_mfma_f32_16x16x32_bf16 v[28:31], v[150:153], v[206:209], v[28:31]
	v_mfma_f32_16x16x32_bf16 v[20:23], v[158:161], v[206:209], v[20:23]
	v_mfma_f32_16x16x32_bf16 v[12:15], v[150:153], v[214:217], v[12:15]
	v_mfma_f32_16x16x32_bf16 v[4:7], v[158:161], v[214:217], v[4:7]
	v_mfma_f32_16x16x32_bf16 v[60:63], v[154:157], v[186:189], v[60:63]
	v_mfma_f32_16x16x32_bf16 v[52:55], v[162:165], v[186:189], v[52:55]
	v_mfma_f32_16x16x32_bf16 v[44:47], v[154:157], v[202:205], v[44:47]
	v_mfma_f32_16x16x32_bf16 v[36:39], v[162:165], v[202:205], v[36:39]
	v_mfma_f32_16x16x32_bf16 v[28:31], v[154:157], v[210:213], v[28:31]
	v_mfma_f32_16x16x32_bf16 v[20:23], v[162:165], v[210:213], v[20:23]
	v_mfma_f32_16x16x32_bf16 v[12:15], v[154:157], v[218:221], v[12:15]
	v_mfma_f32_16x16x32_bf16 v[4:7], v[162:165], v[218:221], v[4:7]
	s_setprio 0
	s_setprio 1
	v_mfma_f32_16x16x32_bf16 v[56:59], v[166:169], v[182:185], v[56:59]
	v_mfma_f32_16x16x32_bf16 v[48:51], v[174:177], v[182:185], v[48:51]
	v_mfma_f32_16x16x32_bf16 v[40:43], v[166:169], v[190:193], v[40:43]
	v_mfma_f32_16x16x32_bf16 v[32:35], v[174:177], v[190:193], v[32:35]
	v_mfma_f32_16x16x32_bf16 v[24:27], v[166:169], v[206:209], v[24:27]
	v_mfma_f32_16x16x32_bf16 v[16:19], v[174:177], v[206:209], v[16:19]
	v_mfma_f32_16x16x32_bf16 v[8:11], v[166:169], v[214:217], v[8:11]
	v_mfma_f32_16x16x32_bf16 v[0:3], v[174:177], v[214:217], v[0:3]
	v_mfma_f32_16x16x32_bf16 v[56:59], v[170:173], v[186:189], v[56:59]
	v_mfma_f32_16x16x32_bf16 v[48:51], v[178:181], v[186:189], v[48:51]
	v_mfma_f32_16x16x32_bf16 v[40:43], v[170:173], v[202:205], v[40:43]
	v_mfma_f32_16x16x32_bf16 v[32:35], v[178:181], v[202:205], v[32:35]
	v_mfma_f32_16x16x32_bf16 v[24:27], v[170:173], v[210:213], v[24:27]
	v_mfma_f32_16x16x32_bf16 v[16:19], v[178:181], v[210:213], v[16:19]
	v_mfma_f32_16x16x32_bf16 v[8:11], v[170:173], v[218:221], v[8:11]
	v_mfma_f32_16x16x32_bf16 v[0:3], v[178:181], v[218:221], v[0:3]
	s_setprio 0
	s_barrier
	s_add_i32 s54, s54, 2
	s_add_u32 s24, s24, 0x100
	s_addc_u32 s25, s25, 0
	s_add_u32 s52, s52, 0x100
	s_addc_u32 s53, s53, 0
	s_cmp_gt_u32 s54, 13
	s_cbranch_scc1 .Lgu_kdone
.LBB0_146:
	s_add_u32 s26, s24, 0xfffc0080
	s_addc_u32 s27, s25, -1
	s_add_i32 s55, 0, 0x10000
	s_cmp_eq_u32 s54, 12
	s_cselect_b32 s29, s17, s27
	s_cselect_b32 s28, s50, s26
	v_add_u32_e32 v140, s55, v143
	s_cselect_b32 s27, s15, s53
	s_cselect_b32 s26, s51, s52
	s_add_i32 s60, 0, 0x14000
	ds_read_b128 v[150:153], v140
	ds_read_b128 v[154:157], v140 offset:1024
	ds_read_b128 v[158:161], v140 offset:2048
	ds_read_b128 v[162:165], v140 offset:3072
	v_add_u32_e32 v140, s60, v143
	ds_read_b128 v[166:169], v140
	ds_read_b128 v[170:173], v140 offset:1024
	ds_read_b128 v[174:177], v140 offset:2048
	ds_read_b128 v[178:181], v140 offset:3072
	s_add_i32 m0, s40, 0xc000
	ds_read_b128 v[182:185], v148
	ds_read_b128 v[186:189], v148 offset:1024
	ds_read_b128 v[190:193], v148 offset:2048
	ds_read_b128 v[202:205], v148 offset:3072
	ds_read_b128 v[206:209], v148 offset:4096
	ds_read_b128 v[210:213], v148 offset:5120
	ds_read_b128 v[214:217], v148 offset:6144
	ds_read_b128 v[218:221], v148 offset:7168
	global_load_lds_dwordx4 v136, s[24:25]
	s_add_i32 m0, s40, 0xe000
	s_nop 0
	global_load_lds_dwordx4 v138, s[24:25]
	s_waitcnt vmcnt(8)
	s_waitcnt lgkmcnt(0)
	s_barrier
	s_setprio 1
	s_waitcnt lgkmcnt(0)
	v_mfma_f32_16x16x32_bf16 v[126:129], v[150:153], v[182:185], v[126:129]
	v_mfma_f32_16x16x32_bf16 v[118:121], v[158:161], v[182:185], v[118:121]
	v_mfma_f32_16x16x32_bf16 v[110:113], v[150:153], v[190:193], v[110:113]
	v_mfma_f32_16x16x32_bf16 v[102:105], v[158:161], v[190:193], v[102:105]
	v_mfma_f32_16x16x32_bf16 v[92:95], v[150:153], v[206:209], v[92:95]
	v_mfma_f32_16x16x32_bf16 v[84:87], v[158:161], v[206:209], v[84:87]
	v_mfma_f32_16x16x32_bf16 v[76:79], v[150:153], v[214:217], v[76:79]
	v_mfma_f32_16x16x32_bf16 v[68:71], v[158:161], v[214:217], v[68:71]
	v_mfma_f32_16x16x32_bf16 v[126:129], v[154:157], v[186:189], v[126:129]
	v_mfma_f32_16x16x32_bf16 v[118:121], v[162:165], v[186:189], v[118:121]
	v_mfma_f32_16x16x32_bf16 v[110:113], v[154:157], v[202:205], v[110:113]
	v_mfma_f32_16x16x32_bf16 v[102:105], v[162:165], v[202:205], v[102:105]
	v_mfma_f32_16x16x32_bf16 v[92:95], v[154:157], v[210:213], v[92:95]
	v_mfma_f32_16x16x32_bf16 v[84:87], v[162:165], v[210:213], v[84:87]
	v_mfma_f32_16x16x32_bf16 v[76:79], v[154:157], v[218:221], v[76:79]
	v_mfma_f32_16x16x32_bf16 v[68:71], v[162:165], v[218:221], v[68:71]
	s_setprio 0
	s_setprio 1
	v_mfma_f32_16x16x32_bf16 v[122:125], v[166:169], v[182:185], v[122:125]
	v_mfma_f32_16x16x32_bf16 v[114:117], v[174:177], v[182:185], v[114:117]
	v_mfma_f32_16x16x32_bf16 v[106:109], v[166:169], v[190:193], v[106:109]
	v_mfma_f32_16x16x32_bf16 v[98:101], v[174:177], v[190:193], v[98:101]
	v_mfma_f32_16x16x32_bf16 v[88:91], v[166:169], v[206:209], v[88:91]
	v_mfma_f32_16x16x32_bf16 v[80:83], v[174:177], v[206:209], v[80:83]
	v_mfma_f32_16x16x32_bf16 v[72:75], v[166:169], v[214:217], v[72:75]
	v_mfma_f32_16x16x32_bf16 v[64:67], v[174:177], v[214:217], v[64:67]
	v_mfma_f32_16x16x32_bf16 v[122:125], v[170:173], v[186:189], v[122:125]
	v_mfma_f32_16x16x32_bf16 v[114:117], v[178:181], v[186:189], v[114:117]
	v_mfma_f32_16x16x32_bf16 v[106:109], v[170:173], v[202:205], v[106:109]
	v_mfma_f32_16x16x32_bf16 v[98:101], v[178:181], v[202:205], v[98:101]
	v_mfma_f32_16x16x32_bf16 v[88:91], v[170:173], v[210:213], v[88:91]
	v_mfma_f32_16x16x32_bf16 v[80:83], v[178:181], v[210:213], v[80:83]
	v_mfma_f32_16x16x32_bf16 v[72:75], v[170:173], v[218:221], v[72:75]
	v_mfma_f32_16x16x32_bf16 v[64:67], v[178:181], v[218:221], v[64:67]
	s_setprio 0
	s_barrier
	s_add_i32 s55, s55, s39
	s_mov_b32 m0, s55
	ds_read_b128 v[182:185], v148 offset:16384
	ds_read_b128 v[186:189], v148 offset:17408
	ds_read_b128 v[190:193], v148 offset:18432
	ds_read_b128 v[202:205], v148 offset:19456
	ds_read_b128 v[206:209], v148 offset:20480
	ds_read_b128 v[210:213], v148 offset:21504
	ds_read_b128 v[214:217], v148 offset:22528
	ds_read_b128 v[218:221], v148 offset:23552
	global_load_lds_dwordx4 v96, s[26:27]
	s_add_i32 m0, s55, 0x2000
	s_add_u32 s56, s26, 0x40000
	s_addc_u32 s57, s27, 0
	s_add_i32 s55, s60, s39
	global_load_lds_dwordx4 v130, s[26:27]
	s_mov_b32 m0, s55
	s_nop 0
	global_load_lds_dwordx4 v96, s[56:57]
	s_add_i32 m0, s55, 0x2000
	s_nop 0
	global_load_lds_dwordx4 v130, s[56:57]
	s_mov_b32 m0, s40
	s_nop 0
	global_load_lds_dwordx4 v134, s[28:29]
	s_mov_b32 m0, s41
	s_nop 0
	global_load_lds_dwordx4 v132, s[28:29]
	s_waitcnt vmcnt(8)
	s_waitcnt lgkmcnt(0)
	s_barrier
	s_setprio 1
	s_waitcnt lgkmcnt(0)
	v_mfma_f32_16x16x32_bf16 v[60:63], v[150:153], v[182:185], v[60:63]
	v_mfma_f32_16x16x32_bf16 v[52:55], v[158:161], v[182:185], v[52:55]
	v_mfma_f32_16x16x32_bf16 v[44:47], v[150:153], v[190:193], v[44:47]
	v_mfma_f32_16x16x32_bf16 v[36:39], v[158:161], v[190:193], v[36:39]
	v_mfma_f32_16x16x32_bf16 v[28:31], v[150:153], v[206:209], v[28:31]
	v_mfma_f32_16x16x32_bf16 v[20:23], v[158:161], v[206:209], v[20:23]
	v_mfma_f32_16x16x32_bf16 v[12:15], v[150:153], v[214:217], v[12:15]
	v_mfma_f32_16x16x32_bf16 v[4:7], v[158:161], v[214:217], v[4:7]
	v_mfma_f32_16x16x32_bf16 v[60:63], v[154:157], v[186:189], v[60:63]
	v_mfma_f32_16x16x32_bf16 v[52:55], v[162:165], v[186:189], v[52:55]
	v_mfma_f32_16x16x32_bf16 v[44:47], v[154:157], v[202:205], v[44:47]
	v_mfma_f32_16x16x32_bf16 v[36:39], v[162:165], v[202:205], v[36:39]
	v_mfma_f32_16x16x32_bf16 v[28:31], v[154:157], v[210:213], v[28:31]
	v_mfma_f32_16x16x32_bf16 v[20:23], v[162:165], v[210:213], v[20:23]
	v_mfma_f32_16x16x32_bf16 v[12:15], v[154:157], v[218:221], v[12:15]
	v_mfma_f32_16x16x32_bf16 v[4:7], v[162:165], v[218:221], v[4:7]
	s_setprio 0
	s_setprio 1
	v_mfma_f32_16x16x32_bf16 v[56:59], v[166:169], v[182:185], v[56:59]
	v_mfma_f32_16x16x32_bf16 v[48:51], v[174:177], v[182:185], v[48:51]
	v_mfma_f32_16x16x32_bf16 v[40:43], v[166:169], v[190:193], v[40:43]
	v_mfma_f32_16x16x32_bf16 v[32:35], v[174:177], v[190:193], v[32:35]
	v_mfma_f32_16x16x32_bf16 v[24:27], v[166:169], v[206:209], v[24:27]
	v_mfma_f32_16x16x32_bf16 v[16:19], v[174:177], v[206:209], v[16:19]
	v_mfma_f32_16x16x32_bf16 v[8:11], v[166:169], v[214:217], v[8:11]
	v_mfma_f32_16x16x32_bf16 v[0:3], v[174:177], v[214:217], v[0:3]
	v_mfma_f32_16x16x32_bf16 v[56:59], v[170:173], v[186:189], v[56:59]
	v_mfma_f32_16x16x32_bf16 v[48:51], v[178:181], v[186:189], v[48:51]
	v_mfma_f32_16x16x32_bf16 v[40:43], v[170:173], v[202:205], v[40:43]
	v_mfma_f32_16x16x32_bf16 v[32:35], v[178:181], v[202:205], v[32:35]
	v_mfma_f32_16x16x32_bf16 v[24:27], v[170:173], v[210:213], v[24:27]
	v_mfma_f32_16x16x32_bf16 v[16:19], v[178:181], v[210:213], v[16:19]
	v_mfma_f32_16x16x32_bf16 v[8:11], v[170:173], v[218:221], v[8:11]
	v_mfma_f32_16x16x32_bf16 v[0:3], v[178:181], v[218:221], v[0:3]
	s_setprio 0
	s_barrier
	s_add_i32 s55, 0, 0x18000
	v_add_u32_e32 v149, s55, v143
	s_add_i32 s56, 0, 0x1c000
	ds_read_b128 v[150:153], v149
	ds_read_b128 v[154:157], v149 offset:1024
	ds_read_b128 v[158:161], v149 offset:2048
	ds_read_b128 v[162:165], v149 offset:3072
	v_add_u32_e32 v149, s56, v143
	ds_read_b128 v[166:169], v149
	ds_read_b128 v[170:173], v149 offset:1024
	ds_read_b128 v[174:177], v149 offset:2048
	ds_read_b128 v[178:181], v149 offset:3072
	s_add_u32 s28, s28, 0x40000
	s_addc_u32 s29, s29, 0
	s_mov_b32 m0, s42
	ds_read_b128 v[182:185], v148 offset:32768
	ds_read_b128 v[186:189], v148 offset:33792
	ds_read_b128 v[190:193], v148 offset:34816
	ds_read_b128 v[202:205], v148 offset:35840
	ds_read_b128 v[206:209], v148 offset:36864
	ds_read_b128 v[210:213], v148 offset:37888
	ds_read_b128 v[214:217], v148 offset:38912
	ds_read_b128 v[218:221], v148 offset:39936
	global_load_lds_dwordx4 v134, s[28:29]
	s_mov_b32 m0, s43
	s_nop 0
	global_load_lds_dwordx4 v132, s[28:29]
	s_waitcnt vmcnt(8)
	s_waitcnt lgkmcnt(0)
	s_barrier
	s_setprio 1
	s_waitcnt lgkmcnt(0)
	v_mfma_f32_16x16x32_bf16 v[126:129], v[150:153], v[182:185], v[126:129]
	v_mfma_f32_16x16x32_bf16 v[118:121], v[158:161], v[182:185], v[118:121]
	v_mfma_f32_16x16x32_bf16 v[110:113], v[150:153], v[190:193], v[110:113]
	v_mfma_f32_16x16x32_bf16 v[102:105], v[158:161], v[190:193], v[102:105]
	v_mfma_f32_16x16x32_bf16 v[92:95], v[150:153], v[206:209], v[92:95]
	v_mfma_f32_16x16x32_bf16 v[84:87], v[158:161], v[206:209], v[84:87]
	v_mfma_f32_16x16x32_bf16 v[76:79], v[150:153], v[214:217], v[76:79]
	v_mfma_f32_16x16x32_bf16 v[68:71], v[158:161], v[214:217], v[68:71]
	v_mfma_f32_16x16x32_bf16 v[126:129], v[154:157], v[186:189], v[126:129]
	v_mfma_f32_16x16x32_bf16 v[118:121], v[162:165], v[186:189], v[118:121]
	v_mfma_f32_16x16x32_bf16 v[110:113], v[154:157], v[202:205], v[110:113]
	v_mfma_f32_16x16x32_bf16 v[102:105], v[162:165], v[202:205], v[102:105]
	v_mfma_f32_16x16x32_bf16 v[92:95], v[154:157], v[210:213], v[92:95]
	v_mfma_f32_16x16x32_bf16 v[84:87], v[162:165], v[210:213], v[84:87]
	v_mfma_f32_16x16x32_bf16 v[76:79], v[154:157], v[218:221], v[76:79]
	v_mfma_f32_16x16x32_bf16 v[68:71], v[162:165], v[218:221], v[68:71]
	s_setprio 0
	s_setprio 1
	v_mfma_f32_16x16x32_bf16 v[122:125], v[166:169], v[182:185], v[122:125]
	v_mfma_f32_16x16x32_bf16 v[114:117], v[174:177], v[182:185], v[114:117]
	v_mfma_f32_16x16x32_bf16 v[106:109], v[166:169], v[190:193], v[106:109]
	v_mfma_f32_16x16x32_bf16 v[98:101], v[174:177], v[190:193], v[98:101]
	v_mfma_f32_16x16x32_bf16 v[88:91], v[166:169], v[206:209], v[88:91]
	v_mfma_f32_16x16x32_bf16 v[80:83], v[174:177], v[206:209], v[80:83]
	v_mfma_f32_16x16x32_bf16 v[72:75], v[166:169], v[214:217], v[72:75]
	v_mfma_f32_16x16x32_bf16 v[64:67], v[174:177], v[214:217], v[64:67]
	v_mfma_f32_16x16x32_bf16 v[122:125], v[170:173], v[186:189], v[122:125]
	v_mfma_f32_16x16x32_bf16 v[114:117], v[178:181], v[186:189], v[114:117]
	v_mfma_f32_16x16x32_bf16 v[106:109], v[170:173], v[202:205], v[106:109]
	v_mfma_f32_16x16x32_bf16 v[98:101], v[178:181], v[202:205], v[98:101]
	v_mfma_f32_16x16x32_bf16 v[88:91], v[170:173], v[210:213], v[88:91]
	v_mfma_f32_16x16x32_bf16 v[80:83], v[178:181], v[210:213], v[80:83]
	v_mfma_f32_16x16x32_bf16 v[72:75], v[170:173], v[218:221], v[72:75]
	v_mfma_f32_16x16x32_bf16 v[64:67], v[178:181], v[218:221], v[64:67]
	s_setprio 0
	s_barrier
	s_add_u32 s98, s28, 0xfffc0080
	s_addc_u32 s99, s29, -1
	s_add_i32 s28, s55, s39
	s_add_u32 s26, s26, 0x80
	s_addc_u32 s27, s27, 0
	s_mov_b32 m0, s28
	ds_read_b128 v[182:185], v148 offset:49152
	ds_read_b128 v[186:189], v148 offset:50176
	ds_read_b128 v[190:193], v148 offset:51200
	ds_read_b128 v[202:205], v148 offset:52224
	ds_read_b128 v[206:209], v148 offset:53248
	ds_read_b128 v[210:213], v148 offset:54272
	ds_read_b128 v[214:217], v148 offset:55296
	ds_read_b128 v[218:221], v148 offset:56320
	global_load_lds_dwordx4 v96, s[26:27]
	s_add_i32 m0, s28, 0x2000
	s_add_i32 s28, s56, s39
	global_load_lds_dwordx4 v130, s[26:27]
	s_add_u32 s26, s26, 0x40000
	s_addc_u32 s27, s27, 0
	s_mov_b32 m0, s28
	s_nop 0
	global_load_lds_dwordx4 v96, s[26:27]
	s_add_i32 m0, s28, 0x2000
	s_nop 0
	global_load_lds_dwordx4 v130, s[26:27]
	s_mov_b32 m0, s44
	s_nop 0
	global_load_lds_dwordx4 v134, s[98:99]
	s_mov_b32 m0, s45
	s_nop 0
	global_load_lds_dwordx4 v132, s[98:99]
	s_waitcnt vmcnt(8)
	s_waitcnt lgkmcnt(0)
	s_barrier
	s_setprio 1
	s_waitcnt lgkmcnt(0)
	v_mfma_f32_16x16x32_bf16 v[60:63], v[150:153], v[182:185], v[60:63]
	v_mfma_f32_16x16x32_bf16 v[52:55], v[158:161], v[182:185], v[52:55]
	v_mfma_f32_16x16x32_bf16 v[44:47], v[150:153], v[190:193], v[44:47]
	v_mfma_f32_16x16x32_bf16 v[36:39], v[158:161], v[190:193], v[36:39]
	v_mfma_f32_16x16x32_bf16 v[28:31], v[150:153], v[206:209], v[28:31]
	v_mfma_f32_16x16x32_bf16 v[20:23], v[158:161], v[206:209], v[20:23]
	v_mfma_f32_16x16x32_bf16 v[12:15], v[150:153], v[214:217], v[12:15]
	v_mfma_f32_16x16x32_bf16 v[4:7], v[158:161], v[214:217], v[4:7]
	v_mfma_f32_16x16x32_bf16 v[60:63], v[154:157], v[186:189], v[60:63]
	v_mfma_f32_16x16x32_bf16 v[52:55], v[162:165], v[186:189], v[52:55]
	v_mfma_f32_16x16x32_bf16 v[44:47], v[154:157], v[202:205], v[44:47]
	v_mfma_f32_16x16x32_bf16 v[36:39], v[162:165], v[202:205], v[36:39]
	v_mfma_f32_16x16x32_bf16 v[28:31], v[154:157], v[210:213], v[28:31]
	v_mfma_f32_16x16x32_bf16 v[20:23], v[162:165], v[210:213], v[20:23]
	v_mfma_f32_16x16x32_bf16 v[12:15], v[154:157], v[218:221], v[12:15]
	v_mfma_f32_16x16x32_bf16 v[4:7], v[162:165], v[218:221], v[4:7]
	s_setprio 0
	s_setprio 1
	v_mfma_f32_16x16x32_bf16 v[56:59], v[166:169], v[182:185], v[56:59]
	v_mfma_f32_16x16x32_bf16 v[48:51], v[174:177], v[182:185], v[48:51]
	v_mfma_f32_16x16x32_bf16 v[40:43], v[166:169], v[190:193], v[40:43]
	v_mfma_f32_16x16x32_bf16 v[32:35], v[174:177], v[190:193], v[32:35]
	v_mfma_f32_16x16x32_bf16 v[24:27], v[166:169], v[206:209], v[24:27]
	v_mfma_f32_16x16x32_bf16 v[16:19], v[174:177], v[206:209], v[16:19]
	v_mfma_f32_16x16x32_bf16 v[8:11], v[166:169], v[214:217], v[8:11]
	v_mfma_f32_16x16x32_bf16 v[0:3], v[174:177], v[214:217], v[0:3]
	v_mfma_f32_16x16x32_bf16 v[56:59], v[170:173], v[186:189], v[56:59]
	v_mfma_f32_16x16x32_bf16 v[48:51], v[178:181], v[186:189], v[48:51]
	v_mfma_f32_16x16x32_bf16 v[40:43], v[170:173], v[202:205], v[40:43]
	v_mfma_f32_16x16x32_bf16 v[32:35], v[178:181], v[202:205], v[32:35]
	v_mfma_f32_16x16x32_bf16 v[24:27], v[170:173], v[210:213], v[24:27]
	v_mfma_f32_16x16x32_bf16 v[16:19], v[178:181], v[210:213], v[16:19]
	v_mfma_f32_16x16x32_bf16 v[8:11], v[170:173], v[218:221], v[8:11]
	v_mfma_f32_16x16x32_bf16 v[0:3], v[178:181], v[218:221], v[0:3]
	s_setprio 0
	s_barrier
	s_add_i32 s54, s54, 2
	s_add_u32 s24, s24, 0x100
	s_addc_u32 s25, s25, 0
	s_add_u32 s52, s52, 0x100
	s_addc_u32 s53, s53, 0
	s_cmp_gt_u32 s54, 13
	s_cbranch_scc0 .LBB0_146
